# NSA item epilogue (RMS-norm + store): all 16 gain-vector loads issued up front into idle registers, one wait instead of twelve sequential load-wait steps
# baseline (speedup 1.0000x reference)
; DEV int opaque_tid() { int t = (int)threadIdx.x; asm volatile("" : "+v"(t)); return t; }
; DEV float lo_f(unsigned w) { return __uint_as_float(w << 16); }
; DEV float hi_f(unsigned w) { return __uint_as_float(w & 0xFFFF0000u); }
; __device__ void nsa_item(const Params& P, int l, int item, char* smem) {
;     ...
;   {
;     const float* gn = P.gn_nsa_g + l * 512;
;     const int tid = opaque_tid(), lane = tid & 63, w = tid >> 6;
;     {
;       const int q = lane & 31, hk = lane >> 5;
;       float tot = 0.f;
; #pragma unroll
;       for (int hh = 0; hh < 8; ++hh) tot += ssq[q * 8 + hh];
;       const float rs = rsqrtf(tot * (1.f / 512.f) + EPS_C);
;       bf16_t* dst = P.CAT + (size_t)(b * SEQ + t0 + q) * 1024 + 512 + w * 64;
;       const float* gh = gn + w * 64;
; #pragma unroll
;       for (int i4 = 0; i4 < 4; ++i4) {
;         const int d = 8 * i4 + 4 * hk;
;         const float4 ga = *(const float4*)(gh + d), gb = *(const float4*)(gh + 32 + d);
;         uint2 o;
;         o.x = pack2(lo_f(ykeep[2 * i4]) * rs * ga.x, hi_f(ykeep[2 * i4]) * rs * ga.y);
;         o.y = pack2(lo_f(ykeep[2 * i4 + 1]) * rs * ga.z, hi_f(ykeep[2 * i4 + 1]) * rs * ga.w);
;         *(uint2*)(dst + d) = o;
;         o.x = pack2(lo_f(ykeep[8 + 2 * i4]) * rs * gb.x, hi_f(ykeep[8 + 2 * i4]) * rs * gb.y);
;         o.y = pack2(lo_f(ykeep[8 + 2 * i4 + 1]) * rs * gb.z, hi_f(ykeep[8 + 2 * i4 + 1]) * rs * gb.w);
;         *(uint2*)(dst + 32 + d) = o;
;       }
.LBB0_148:
	v_mov_b32_e32 v1, v202
	s_mov_b32 s0, 0x800000
	v_and_b32_e32 v8, 31, v1
	v_lshlrev_b32_e32 v0, 5, v8
	ds_read_b128 v[2:5], v0 offset:32768
	ds_read_b128 v[10:13], v0 offset:32784
	v_lshrrev_b32_e32 v6, 3, v1
	v_and_b32_e32 v9, 4, v6
	v_lshlrev_b32_e32 v20, 2, v8
	s_waitcnt lgkmcnt(1)
	v_add_f32_e32 v0, 0, v2
	v_add_f32_e32 v0, v0, v3
	v_add_f32_e32 v0, v0, v4
	v_add_f32_e32 v0, v0, v5
	s_waitcnt lgkmcnt(0)
	v_add_f32_e32 v0, v0, v10
	v_add_f32_e32 v0, v0, v11
	v_add_f32_e32 v0, v0, v12
	v_add_f32_e32 v0, v0, v13
	v_fmamk_f32 v0, v0, 0x3b000000, v203
	v_cmp_gt_f32_e32 vcc, s0, v0
	v_mul_f32_e32 v2, 0x4b800000, v0
	v_readlane_b32 s0, v248, 42
	v_cndmask_b32_e32 v0, v0, v2, vcc
	v_rsq_f32_e32 v0, v0
	s_or_b32 s0, s50, s0
	v_and_b32_e32 v4, 0xffffffc0, v1
	v_ashrrev_i32_e32 v5, 31, v4
	v_mul_f32_e32 v2, 0x45800000, v0
	v_cndmask_b32_e32 v0, v0, v2, vcc
	v_or_b32_e32 v2, s0, v8
	v_lshlrev_b32_e32 v176, 11, v2
	v_readlane_b32 s0, v248, 11
	v_lshl_add_u64 v[2:3], s[30:31], 0, v[176:177]
	v_readlane_b32 s1, v248, 12
	v_and_b32_e32 v14, 0xffffffe0, v1
	v_mov_b32_e32 v15, v177
	v_lshl_add_u64 v[14:15], v[14:15], 2, s[0:1]
	global_load_dwordx4 v[68:71], v[14:15], off offset:1040
	global_load_dwordx4 v[72:75], v[14:15], off offset:1024
	global_load_dwordx4 v[76:79], v[14:15], off offset:1072
	global_load_dwordx4 v[80:83], v[14:15], off offset:1056
	global_load_dwordx4 v[96:99], v[14:15], off offset:1104
	global_load_dwordx4 v[100:103], v[14:15], off offset:1088
	global_load_dwordx4 v[104:107], v[14:15], off offset:1136
	global_load_dwordx4 v[108:111], v[14:15], off offset:1120
	v_lshl_add_u64 v[14:15], v[4:5], 1, v[2:3]
	v_lshlrev_b32_e32 v176, 2, v9
	v_lshl_add_u64 v[4:5], v[4:5], 2, s[0:1]
	v_lshl_add_u64 v[6:7], v[4:5], 0, v[176:177]
	global_load_dwordx4 v[36:39], v[6:7], off
	global_load_dwordx4 v[40:43], v[6:7], off offset:128
	global_load_dwordx4 v[44:47], v[6:7], off offset:32
	global_load_dwordx4 v[48:51], v[6:7], off offset:160
	global_load_dwordx4 v[52:55], v[6:7], off offset:64
	global_load_dwordx4 v[56:59], v[6:7], off offset:192
	global_load_dwordx4 v[60:63], v[6:7], off offset:96
	global_load_dwordx4 v[64:67], v[6:7], off offset:224
	v_lshlrev_b32_e32 v4, 16, v112
	v_and_b32_e32 v5, 0xffff0000, v112
	v_pk_mul_f32 v[4:5], v[0:1], v[4:5] op_sel_hi:[0, 1]
	v_lshlrev_b32_e32 v176, 1, v9
	v_readlane_b32 s60, v249, 15
	v_readlane_b32 s61, v249, 16
	v_readlane_b32 s62, v249, 17
	v_readlane_b32 s63, v249, 18
	s_waitcnt vmcnt(0)
	v_pk_mul_f32 v[4:5], v[36:37], v[4:5]
	s_nop 0
	v_cvt_pk_bf16_f32 v18, v4, v5
	v_lshlrev_b32_e32 v4, 16, v95
	v_and_b32_e32 v5, 0xffff0000, v95
	v_pk_mul_f32 v[4:5], v[0:1], v[4:5] op_sel_hi:[0, 1]
	v_pk_mul_f32 v[4:5], v[38:39], v[4:5]
	v_cvt_pk_bf16_f32 v19, v4, v5
	v_lshl_add_u64 v[4:5], v[14:15], 0, v[176:177]
	v_lshlrev_b32_e32 v14, 16, v94
	v_and_b32_e32 v15, 0xffff0000, v94
	v_pk_mul_f32 v[14:15], v[0:1], v[14:15] op_sel_hi:[0, 1]
	global_store_dwordx2 v[4:5], v[18:19], off offset:1024
	v_lshlrev_b32_e32 v18, 16, v90
	v_and_b32_e32 v19, 0xffff0000, v90
	v_pk_mul_f32 v[18:19], v[0:1], v[18:19] op_sel_hi:[0, 1]
	v_pk_mul_f32 v[10:11], v[40:41], v[14:15]
	v_lshlrev_b32_e32 v14, 16, v93
	v_and_b32_e32 v15, 0xffff0000, v93
	v_pk_mul_f32 v[14:15], v[0:1], v[14:15] op_sel_hi:[0, 1]
	v_pk_mul_f32 v[12:13], v[42:43], v[14:15]
	v_cvt_pk_bf16_f32 v10, v10, v11
	v_cvt_pk_bf16_f32 v11, v12, v13
	global_store_dwordx2 v[4:5], v[10:11], off offset:1088
	v_lshlrev_b32_e32 v14, 16, v92
	v_and_b32_e32 v15, 0xffff0000, v92
	v_pk_mul_f32 v[14:15], v[0:1], v[14:15] op_sel_hi:[0, 1]
	v_pk_mul_f32 v[10:11], v[14:15], v[44:45]
	s_nop 0
	v_cvt_pk_bf16_f32 v14, v10, v11
	v_lshlrev_b32_e32 v10, 16, v91
	v_and_b32_e32 v11, 0xffff0000, v91
	v_pk_mul_f32 v[10:11], v[0:1], v[10:11] op_sel_hi:[0, 1]
	v_pk_mul_f32 v[10:11], v[10:11], v[46:47]
	s_nop 0
	v_cvt_pk_bf16_f32 v15, v10, v11
	v_pk_mul_f32 v[10:11], v[18:19], v[48:49]
	v_lshlrev_b32_e32 v18, 16, v89
	v_and_b32_e32 v19, 0xffff0000, v89
	global_store_dwordx2 v[4:5], v[14:15], off offset:1040
	v_pk_mul_f32 v[14:15], v[0:1], v[18:19] op_sel_hi:[0, 1]
	v_pk_mul_f32 v[12:13], v[14:15], v[50:51]
	v_cvt_pk_bf16_f32 v10, v10, v11
	v_cvt_pk_bf16_f32 v11, v12, v13
	global_store_dwordx2 v[4:5], v[10:11], off offset:1104
	v_lshlrev_b32_e32 v14, 16, v88
	v_and_b32_e32 v15, 0xffff0000, v88
	v_pk_mul_f32 v[14:15], v[0:1], v[14:15] op_sel_hi:[0, 1]
	v_lshlrev_b32_e32 v18, 16, v86
	v_and_b32_e32 v19, 0xffff0000, v86
	v_pk_mul_f32 v[18:19], v[0:1], v[18:19] op_sel_hi:[0, 1]
	v_pk_mul_f32 v[10:11], v[14:15], v[52:53]
	s_nop 0
	v_cvt_pk_bf16_f32 v14, v10, v11
	v_lshlrev_b32_e32 v10, 16, v87
	v_and_b32_e32 v11, 0xffff0000, v87
	v_pk_mul_f32 v[10:11], v[0:1], v[10:11] op_sel_hi:[0, 1]
	v_pk_mul_f32 v[10:11], v[10:11], v[54:55]
	s_nop 0
	v_cvt_pk_bf16_f32 v15, v10, v11
	v_pk_mul_f32 v[10:11], v[18:19], v[56:57]
	v_lshlrev_b32_e32 v18, 16, v85
	v_and_b32_e32 v19, 0xffff0000, v85
	global_store_dwordx2 v[4:5], v[14:15], off offset:1056
	v_pk_mul_f32 v[14:15], v[0:1], v[18:19] op_sel_hi:[0, 1]
	v_pk_mul_f32 v[12:13], v[14:15], v[58:59]
	v_cvt_pk_bf16_f32 v10, v10, v11
	v_cvt_pk_bf16_f32 v11, v12, v13
	global_store_dwordx2 v[4:5], v[10:11], off offset:1120
	v_lshlrev_b32_e32 v14, 16, v84
	v_and_b32_e32 v15, 0xffff0000, v84
	v_pk_mul_f32 v[14:15], v[0:1], v[14:15] op_sel_hi:[0, 1]
	v_lshlrev_b32_e32 v18, 16, v33
	v_and_b32_e32 v19, 0xffff0000, v33
	v_pk_mul_f32 v[10:11], v[14:15], v[60:61]
	s_nop 0
	v_cvt_pk_bf16_f32 v14, v10, v11
	v_lshlrev_b32_e32 v10, 16, v35
	v_and_b32_e32 v11, 0xffff0000, v35
	v_pk_mul_f32 v[10:11], v[0:1], v[10:11] op_sel_hi:[0, 1]
	v_pk_mul_f32 v[10:11], v[10:11], v[62:63]
	s_nop 0
	v_cvt_pk_bf16_f32 v15, v10, v11
	v_pk_mul_f32 v[6:7], v[0:1], v[18:19] op_sel_hi:[0, 1]
	global_store_dwordx2 v[4:5], v[14:15], off offset:1072
	v_and_b32_e32 v14, 0xffffffe0, v1
	v_lshl_or_b32 v21, v14, 7, v20
	v_ashrrev_i32_e32 v15, 31, v14
	v_lshl_add_u64 v[2:3], v[14:15], 1, v[2:3]
	v_pk_mul_f32 v[6:7], v[6:7], v[64:65]
	v_lshlrev_b32_e32 v10, 16, v16
	v_and_b32_e32 v11, 0xffff0000, v16
	v_pk_mul_f32 v[10:11], v[0:1], v[10:11] op_sel_hi:[0, 1]
	v_pk_mul_f32 v[10:11], v[10:11], v[66:67]
	v_cvt_pk_bf16_f32 v6, v6, v7
	v_cvt_pk_bf16_f32 v7, v10, v11
	global_store_dwordx2 v[4:5], v[6:7], off offset:1136
	ds_read2_b32 v[6:7], v21 offset1:32
	v_lshl_add_u64 v[4:5], v[14:15], 2, s[0:1]
	s_movk_i32 s0, 0xf80
	s_waitcnt lgkmcnt(0)
; __device__ void nsa_item(const Params& P, int l, int item, char* smem) {
;     ...
;     {
;       const int q2 = tid & 31, cg8 = tid >> 5;
;       float tot = 0.f;
; #pragma unroll
;       for (int hh = 0; hh < 8; ++hh) tot += ssq[q2 * 8 + hh];
;       const float rs = rsqrtf(tot * (1.f / 512.f) + EPS_C);
;       bf16_t* dst = P.CAT + (size_t)(b * SEQ + t0 + q2) * 1024 + 512 + 256;
; #pragma unroll
;       for (int c8 = 0; c8 < 4; ++c8) {
;         const int cl = cg8 * 32 + c8 * 8;
;         float o1[8];
; #pragma unroll
;         for (int k = 0; k < 8; ++k) o1[k] = yacc[(cl + k) * 32 + q2] * rs * gn[256 + cl + k];
;         *(bf16x8*)(dst + cl) = pack8(o1);
;       }
	v_pk_mul_f32 v[16:17], v[0:1], v[6:7] op_sel_hi:[0, 1]
	v_pk_mul_f32 v[10:11], v[72:73], v[16:17]
	ds_read2_b32 v[16:17], v21 offset0:64 offset1:96
	s_waitcnt lgkmcnt(0)
	v_pk_mul_f32 v[16:17], v[0:1], v[16:17] op_sel_hi:[0, 1]
	v_pk_mul_f32 v[12:13], v[74:75], v[16:17]
	ds_read2_b32 v[16:17], v21 offset0:128 offset1:160
	s_waitcnt lgkmcnt(0)
	v_pk_mul_f32 v[16:17], v[0:1], v[16:17] op_sel_hi:[0, 1]
	v_pk_mul_f32 v[16:17], v[16:17], v[68:69]
	ds_read2_b32 v[6:7], v21 offset0:192 offset1:224
	s_waitcnt lgkmcnt(0)
	v_pk_mul_f32 v[6:7], v[0:1], v[6:7] op_sel_hi:[0, 1]
	v_pk_mul_f32 v[18:19], v[6:7], v[70:71]
	v_cvt_pk_bf16_f32 v6, v10, v11
	v_cvt_pk_bf16_f32 v7, v12, v13
	v_cvt_pk_bf16_f32 v8, v16, v17
	v_cvt_pk_bf16_f32 v9, v18, v19
	v_add_u32_e32 v16, 0x400, v21
	global_store_dwordx4 v[2:3], v[6:9], off offset:1536
	ds_read2_b32 v[6:7], v16 offset1:32
	s_waitcnt lgkmcnt(0)
	v_pk_mul_f32 v[14:15], v[0:1], v[6:7] op_sel_hi:[0, 1]
	v_pk_mul_f32 v[10:11], v[14:15], v[80:81]
	ds_read2_b32 v[14:15], v16 offset0:64 offset1:96
	s_waitcnt lgkmcnt(0)
	v_pk_mul_f32 v[14:15], v[0:1], v[14:15] op_sel_hi:[0, 1]
	v_pk_mul_f32 v[12:13], v[14:15], v[82:83]
	ds_read2_b32 v[14:15], v16 offset0:128 offset1:160
	s_waitcnt lgkmcnt(0)
	v_pk_mul_f32 v[14:15], v[0:1], v[14:15] op_sel_hi:[0, 1]
	v_pk_mul_f32 v[14:15], v[14:15], v[76:77]
	ds_read2_b32 v[6:7], v16 offset0:192 offset1:224
	s_waitcnt lgkmcnt(0)
	v_pk_mul_f32 v[6:7], v[0:1], v[6:7] op_sel_hi:[0, 1]
	v_pk_mul_f32 v[16:17], v[6:7], v[78:79]
	v_cvt_pk_bf16_f32 v6, v10, v11
	v_cvt_pk_bf16_f32 v7, v12, v13
	v_cvt_pk_bf16_f32 v8, v14, v15
	v_cvt_pk_bf16_f32 v9, v16, v17
	v_add_u32_e32 v16, 0x800, v21
	global_store_dwordx4 v[2:3], v[6:9], off offset:1552
	ds_read2_b32 v[6:7], v16 offset1:32
	s_waitcnt lgkmcnt(0)
	v_pk_mul_f32 v[14:15], v[0:1], v[6:7] op_sel_hi:[0, 1]
	v_pk_mul_f32 v[10:11], v[14:15], v[100:101]
	ds_read2_b32 v[14:15], v16 offset0:64 offset1:96
	s_waitcnt lgkmcnt(0)
	v_pk_mul_f32 v[14:15], v[0:1], v[14:15] op_sel_hi:[0, 1]
	v_pk_mul_f32 v[12:13], v[14:15], v[102:103]
	ds_read2_b32 v[14:15], v16 offset0:128 offset1:160
	s_waitcnt lgkmcnt(0)
	v_pk_mul_f32 v[14:15], v[0:1], v[14:15] op_sel_hi:[0, 1]
	v_pk_mul_f32 v[14:15], v[14:15], v[96:97]
	ds_read2_b32 v[6:7], v16 offset0:192 offset1:224
	s_waitcnt lgkmcnt(0)
	v_pk_mul_f32 v[6:7], v[0:1], v[6:7] op_sel_hi:[0, 1]
	v_pk_mul_f32 v[16:17], v[6:7], v[98:99]
	v_cvt_pk_bf16_f32 v6, v10, v11
	v_cvt_pk_bf16_f32 v7, v12, v13
	v_cvt_pk_bf16_f32 v8, v14, v15
	v_cvt_pk_bf16_f32 v9, v16, v17
	v_add_u32_e32 v16, 0xc00, v21
	global_store_dwordx4 v[2:3], v[6:9], off offset:1568
	ds_read2_b32 v[6:7], v16 offset1:32
	s_waitcnt lgkmcnt(0)
	v_pk_mul_f32 v[14:15], v[0:1], v[6:7] op_sel_hi:[0, 1]
	v_pk_mul_f32 v[4:5], v[14:15], v[108:109]
	ds_read2_b32 v[10:11], v16 offset0:64 offset1:96
	v_cvt_pk_bf16_f32 v4, v4, v5
	s_waitcnt lgkmcnt(0)
	v_pk_mul_f32 v[10:11], v[0:1], v[10:11] op_sel_hi:[0, 1]
	v_pk_mul_f32 v[10:11], v[10:11], v[110:111]
	ds_read2_b32 v[12:13], v16 offset0:128 offset1:160
	v_cvt_pk_bf16_f32 v5, v10, v11
	s_waitcnt lgkmcnt(0)
	v_pk_mul_f32 v[12:13], v[0:1], v[12:13] op_sel_hi:[0, 1]
	v_lshlrev_b32_e32 v1, 7, v1
	v_or3_b32 v1, v1, v20, s0
	v_pk_mul_f32 v[6:7], v[12:13], v[104:105]
	ds_read_b32 v12, v21 offset:3840
	ds_read_b32 v13, v1
	v_cvt_pk_bf16_f32 v6, v6, v7
	s_mov_b64 s[0:1], 0
	s_waitcnt lgkmcnt(0)
	v_pk_mul_f32 v[0:1], v[0:1], v[12:13] op_sel_hi:[0, 1]
	v_pk_mul_f32 v[0:1], v[0:1], v[106:107]
	s_nop 0
	v_cvt_pk_bf16_f32 v7, v0, v1
	global_store_dwordx4 v[2:3], v[4:7], off offset:1584
	s_barrier
